# LRU pass-2 tile order: the 16 tiles of the second round are the context tiles (short carry-in); first round = the 256 latent tiles
# speedup vs baseline: 1.0083x; 1.0049x over previous
.LBB0_268:
	v_readlane_b32 s6, v255, 10
	v_readlane_b32 s7, v255, 11
	s_andn2_b64 vcc, exec, s[6:7]
	s_mov_b64 s[6:7], -1
	s_cbranch_vccnz .LBB0_270
	s_cmp_lt_i32 s57, 0x100
	s_cbranch_scc1 .LBB0_270
	s_sub_i32 s6, s57, 0x100
	s_ashr_i32 s40, s6, 2
	s_and_b32 s48, s6, 3
	s_mov_b64 s[6:7], 0
